# P6 up-projection K loop: the per-segment s_setprio 1/0 flips around the MFMA blocks removed (both wave groups at equal priority)
# speedup vs baseline: 1.0046x; 1.0046x over previous
.LBB0_2359:
	ds_read_b128 v[150:153], v192
	ds_read_b128 v[154:157], v192 offset:1024
	ds_read_b128 v[158:161], v192 offset:2048
	ds_read_b128 v[172:175], v192 offset:3072
	v_add_u32_e32 v148, 0xc000, v183
	v_lshl_add_u64 v[180:181], s[62:63], 0, v[138:139]
	v_readfirstlane_b32 s61, v148
	v_add_u32_e32 v149, 0xe000, v183
	v_lshl_add_u64 v[230:231], v[180:181], 0, s[18:19]
	s_mov_b32 m0, s61
	v_lshl_add_u64 v[246:247], s[62:63], 0, v[140:141]
	v_readfirstlane_b32 s61, v149
	ds_read_b128 v[176:179], v193
	ds_read_b128 v[202:205], v193 offset:1024
	ds_read_b128 v[206:209], v194
	ds_read_b128 v[210:213], v194 offset:1024
	ds_read_b128 v[214:217], v195
	ds_read_b128 v[218:221], v195 offset:1024
	ds_read_b128 v[222:225], v196
	ds_read_b128 v[226:229], v196 offset:1024
	global_load_lds_dwordx4 v[230:231], off
	v_lshl_add_u64 v[230:231], v[246:247], 0, s[18:19]
	s_mov_b32 m0, s61
	s_nop 0
	global_load_lds_dwordx4 v[230:231], off
	s_waitcnt lgkmcnt(8)
	s_barrier
	s_waitcnt lgkmcnt(0)
	s_waitcnt lgkmcnt(0)
	v_mfma_f32_16x16x32_bf16 v[126:129], v[150:153], v[176:179], v[126:129]
	v_mfma_f32_16x16x32_bf16 v[122:125], v[158:161], v[176:179], v[122:125]
	v_mfma_f32_16x16x32_bf16 v[118:121], v[150:153], v[206:209], v[118:121]
	v_mfma_f32_16x16x32_bf16 v[114:117], v[158:161], v[206:209], v[114:117]
	v_mfma_f32_16x16x32_bf16 v[110:113], v[150:153], v[214:217], v[110:113]
	v_mfma_f32_16x16x32_bf16 v[106:109], v[158:161], v[214:217], v[106:109]
	v_mfma_f32_16x16x32_bf16 v[102:105], v[150:153], v[222:225], v[102:105]
	v_mfma_f32_16x16x32_bf16 v[98:101], v[158:161], v[222:225], v[98:101]
	v_mfma_f32_16x16x32_bf16 v[126:129], v[154:157], v[202:205], v[126:129]
	v_mfma_f32_16x16x32_bf16 v[122:125], v[172:175], v[202:205], v[122:125]
	v_mfma_f32_16x16x32_bf16 v[118:121], v[154:157], v[210:213], v[118:121]
	v_mfma_f32_16x16x32_bf16 v[114:117], v[172:175], v[210:213], v[114:117]
	v_mfma_f32_16x16x32_bf16 v[110:113], v[154:157], v[218:221], v[110:113]
	v_mfma_f32_16x16x32_bf16 v[106:109], v[172:175], v[218:221], v[106:109]
	v_mfma_f32_16x16x32_bf16 v[102:105], v[154:157], v[226:229], v[102:105]
	v_mfma_f32_16x16x32_bf16 v[98:101], v[172:175], v[226:229], v[98:101]
	s_barrier
	v_lshl_add_u64 v[248:249], s[62:63], 0, v[134:135]
	v_readfirstlane_b32 s61, v188
	v_lshl_add_u64 v[250:251], v[248:249], 0, s[20:21]
	s_mov_b32 m0, s61
	ds_read_b128 v[230:233], v197
	ds_read_b128 v[234:237], v197 offset:1024
	ds_read_b128 v[238:241], v197 offset:2048
	ds_read_b128 v[242:245], v197 offset:3072
	global_load_lds_dwordx4 v[250:251], off
	v_lshl_add_u64 v[250:251], s[62:63], 0, v[136:137]
	v_readfirstlane_b32 s61, v189
	v_lshl_add_u64 v[252:253], v[250:251], 0, s[20:21]
	s_mov_b32 m0, s61
	s_nop 0
	global_load_lds_dwordx4 v[252:253], off
	s_barrier
	s_waitcnt lgkmcnt(0)
	s_waitcnt lgkmcnt(0)
	v_mfma_f32_16x16x32_bf16 v[94:97], v[230:233], v[176:179], v[94:97]
	v_mfma_f32_16x16x32_bf16 v[90:93], v[238:241], v[176:179], v[90:93]
	v_mfma_f32_16x16x32_bf16 v[86:89], v[230:233], v[206:209], v[86:89]
	v_mfma_f32_16x16x32_bf16 v[82:85], v[238:241], v[206:209], v[82:85]
	v_mfma_f32_16x16x32_bf16 v[78:81], v[230:233], v[214:217], v[78:81]
	v_mfma_f32_16x16x32_bf16 v[74:77], v[238:241], v[214:217], v[74:77]
	v_mfma_f32_16x16x32_bf16 v[70:73], v[230:233], v[222:225], v[70:73]
	v_mfma_f32_16x16x32_bf16 v[66:69], v[238:241], v[222:225], v[66:69]
	v_mfma_f32_16x16x32_bf16 v[94:97], v[234:237], v[202:205], v[94:97]
	v_mfma_f32_16x16x32_bf16 v[90:93], v[242:245], v[202:205], v[90:93]
	v_mfma_f32_16x16x32_bf16 v[86:89], v[234:237], v[210:213], v[86:89]
	v_mfma_f32_16x16x32_bf16 v[82:85], v[242:245], v[210:213], v[82:85]
	v_mfma_f32_16x16x32_bf16 v[78:81], v[234:237], v[218:221], v[78:81]
	v_mfma_f32_16x16x32_bf16 v[74:77], v[242:245], v[218:221], v[74:77]
	v_mfma_f32_16x16x32_bf16 v[70:73], v[234:237], v[226:229], v[70:73]
	v_mfma_f32_16x16x32_bf16 v[66:69], v[242:245], v[226:229], v[66:69]
	v_readfirstlane_b32 s61, v183
	v_lshl_add_u64 v[252:253], v[180:181], 0, s[22:23]
	s_mov_b32 m0, s61
	v_readfirstlane_b32 s61, v184
	s_barrier
	ds_read_b128 v[176:179], v193 offset:16384
	ds_read_b128 v[202:205], v193 offset:17408
	ds_read_b128 v[206:209], v194 offset:16384
	ds_read_b128 v[210:213], v194 offset:17408
	ds_read_b128 v[214:217], v195 offset:16384
	ds_read_b128 v[218:221], v195 offset:17408
	ds_read_b128 v[222:225], v196 offset:16384
	ds_read_b128 v[226:229], v196 offset:17408
	global_load_lds_dwordx4 v[252:253], off
	v_lshl_add_u64 v[252:253], v[246:247], 0, s[22:23]
	s_mov_b32 m0, s61
	s_nop 0
	global_load_lds_dwordx4 v[252:253], off
	s_barrier
	s_waitcnt lgkmcnt(0)
	s_waitcnt lgkmcnt(0)
	v_mfma_f32_16x16x32_bf16 v[62:65], v[150:153], v[176:179], v[62:65]
	v_mfma_f32_16x16x32_bf16 v[58:61], v[158:161], v[176:179], v[58:61]
	v_mfma_f32_16x16x32_bf16 v[54:57], v[150:153], v[206:209], v[54:57]
	v_mfma_f32_16x16x32_bf16 v[50:53], v[158:161], v[206:209], v[50:53]
	v_mfma_f32_16x16x32_bf16 v[46:49], v[150:153], v[214:217], v[46:49]
	v_mfma_f32_16x16x32_bf16 v[42:45], v[158:161], v[214:217], v[42:45]
	v_mfma_f32_16x16x32_bf16 v[38:41], v[150:153], v[222:225], v[38:41]
	v_mfma_f32_16x16x32_bf16 v[34:37], v[158:161], v[222:225], v[34:37]
	v_mfma_f32_16x16x32_bf16 v[62:65], v[154:157], v[202:205], v[62:65]
	v_mfma_f32_16x16x32_bf16 v[58:61], v[172:175], v[202:205], v[58:61]
	v_mfma_f32_16x16x32_bf16 v[54:57], v[154:157], v[210:213], v[54:57]
	v_mfma_f32_16x16x32_bf16 v[50:53], v[172:175], v[210:213], v[50:53]
	v_mfma_f32_16x16x32_bf16 v[46:49], v[154:157], v[218:221], v[46:49]
	v_mfma_f32_16x16x32_bf16 v[42:45], v[172:175], v[218:221], v[42:45]
	v_mfma_f32_16x16x32_bf16 v[38:41], v[154:157], v[226:229], v[38:41]
	v_mfma_f32_16x16x32_bf16 v[34:37], v[172:175], v[226:229], v[34:37]
	s_barrier
	v_readfirstlane_b32 s61, v190
	v_lshl_add_u64 v[150:151], v[248:249], 0, s[24:25]
	s_mov_b32 m0, s61
	v_readfirstlane_b32 s61, v191
	global_load_lds_dwordx4 v[150:151], off
	v_lshl_add_u64 v[150:151], v[250:251], 0, s[24:25]
	s_mov_b32 m0, s61
	s_nop 0
	global_load_lds_dwordx4 v[150:151], off
	s_waitcnt vmcnt(6)
	s_barrier
	v_mfma_f32_16x16x32_bf16 v[30:33], v[230:233], v[176:179], v[30:33]
	v_mfma_f32_16x16x32_bf16 v[26:29], v[238:241], v[176:179], v[26:29]
	v_mfma_f32_16x16x32_bf16 v[22:25], v[230:233], v[206:209], v[22:25]
	v_mfma_f32_16x16x32_bf16 v[18:21], v[238:241], v[206:209], v[18:21]
	v_mfma_f32_16x16x32_bf16 v[14:17], v[230:233], v[214:217], v[14:17]
	v_mfma_f32_16x16x32_bf16 v[10:13], v[238:241], v[214:217], v[10:13]
	v_mfma_f32_16x16x32_bf16 v[6:9], v[230:233], v[222:225], v[6:9]
	v_mfma_f32_16x16x32_bf16 v[2:5], v[238:241], v[222:225], v[2:5]
	v_mfma_f32_16x16x32_bf16 v[30:33], v[234:237], v[202:205], v[30:33]
	v_mfma_f32_16x16x32_bf16 v[26:29], v[242:245], v[202:205], v[26:29]
	v_mfma_f32_16x16x32_bf16 v[22:25], v[234:237], v[210:213], v[22:25]
	v_mfma_f32_16x16x32_bf16 v[18:21], v[242:245], v[210:213], v[18:21]
	v_mfma_f32_16x16x32_bf16 v[14:17], v[234:237], v[218:221], v[14:17]
	v_mfma_f32_16x16x32_bf16 v[10:13], v[242:245], v[218:221], v[10:13]
	v_mfma_f32_16x16x32_bf16 v[6:9], v[234:237], v[226:229], v[6:9]
	v_mfma_f32_16x16x32_bf16 v[2:5], v[242:245], v[226:229], v[2:5]
	s_barrier
	ds_read_b128 v[150:153], v199
	ds_read_b128 v[154:157], v199 offset:1024
	ds_read_b128 v[158:161], v199 offset:2048
	ds_read_b128 v[172:175], v199 offset:3072
	v_readfirstlane_b32 s61, v185
	v_lshl_add_u64 v[230:231], v[180:181], 0, s[26:27]
	s_mov_b32 m0, s61
	v_readfirstlane_b32 s61, v186
	ds_read_b128 v[176:179], v193 offset:32768
	ds_read_b128 v[202:205], v193 offset:33792
	ds_read_b128 v[206:209], v194 offset:32768
	ds_read_b128 v[210:213], v194 offset:33792
	ds_read_b128 v[214:217], v195 offset:32768
	ds_read_b128 v[218:221], v195 offset:33792
	ds_read_b128 v[222:225], v196 offset:32768
	ds_read_b128 v[226:229], v196 offset:33792
	global_load_lds_dwordx4 v[230:231], off
	v_lshl_add_u64 v[230:231], v[246:247], 0, s[26:27]
	s_mov_b32 m0, s61
	s_nop 0
	global_load_lds_dwordx4 v[230:231], off
	s_waitcnt lgkmcnt(8)
	s_barrier
	s_waitcnt lgkmcnt(0)
	s_waitcnt lgkmcnt(0)
	v_mfma_f32_16x16x32_bf16 v[126:129], v[150:153], v[176:179], v[126:129]
	v_mfma_f32_16x16x32_bf16 v[122:125], v[158:161], v[176:179], v[122:125]
	v_mfma_f32_16x16x32_bf16 v[118:121], v[150:153], v[206:209], v[118:121]
	v_mfma_f32_16x16x32_bf16 v[114:117], v[158:161], v[206:209], v[114:117]
	v_mfma_f32_16x16x32_bf16 v[110:113], v[150:153], v[214:217], v[110:113]
	v_mfma_f32_16x16x32_bf16 v[106:109], v[158:161], v[214:217], v[106:109]
	v_mfma_f32_16x16x32_bf16 v[102:105], v[150:153], v[222:225], v[102:105]
	v_mfma_f32_16x16x32_bf16 v[98:101], v[158:161], v[222:225], v[98:101]
	v_mfma_f32_16x16x32_bf16 v[126:129], v[154:157], v[202:205], v[126:129]
	v_mfma_f32_16x16x32_bf16 v[122:125], v[172:175], v[202:205], v[122:125]
	v_mfma_f32_16x16x32_bf16 v[118:121], v[154:157], v[210:213], v[118:121]
	v_mfma_f32_16x16x32_bf16 v[114:117], v[172:175], v[210:213], v[114:117]
	v_mfma_f32_16x16x32_bf16 v[110:113], v[154:157], v[218:221], v[110:113]
	v_mfma_f32_16x16x32_bf16 v[106:109], v[172:175], v[218:221], v[106:109]
	v_mfma_f32_16x16x32_bf16 v[102:105], v[154:157], v[226:229], v[102:105]
	v_mfma_f32_16x16x32_bf16 v[98:101], v[172:175], v[226:229], v[98:101]
	s_barrier
	v_readfirstlane_b32 s61, v142
	v_lshl_add_u64 v[252:253], v[248:249], 0, s[28:29]
	s_mov_b32 m0, s61
	v_readfirstlane_b32 s61, v143
	ds_read_b128 v[230:233], v200
	ds_read_b128 v[234:237], v200 offset:1024
	ds_read_b128 v[238:241], v200 offset:2048
	ds_read_b128 v[242:245], v200 offset:3072
	global_load_lds_dwordx4 v[252:253], off
	v_lshl_add_u64 v[252:253], v[250:251], 0, s[28:29]
	s_mov_b32 m0, s61
	s_nop 0
	global_load_lds_dwordx4 v[252:253], off
	s_barrier
	s_waitcnt lgkmcnt(0)
	s_waitcnt lgkmcnt(0)
	v_mfma_f32_16x16x32_bf16 v[94:97], v[230:233], v[176:179], v[94:97]
	v_mfma_f32_16x16x32_bf16 v[90:93], v[238:241], v[176:179], v[90:93]
	v_mfma_f32_16x16x32_bf16 v[86:89], v[230:233], v[206:209], v[86:89]
	v_mfma_f32_16x16x32_bf16 v[82:85], v[238:241], v[206:209], v[82:85]
	v_mfma_f32_16x16x32_bf16 v[78:81], v[230:233], v[214:217], v[78:81]
	v_mfma_f32_16x16x32_bf16 v[74:77], v[238:241], v[214:217], v[74:77]
	v_mfma_f32_16x16x32_bf16 v[70:73], v[230:233], v[222:225], v[70:73]
	v_mfma_f32_16x16x32_bf16 v[66:69], v[238:241], v[222:225], v[66:69]
	v_mfma_f32_16x16x32_bf16 v[94:97], v[234:237], v[202:205], v[94:97]
	v_mfma_f32_16x16x32_bf16 v[90:93], v[242:245], v[202:205], v[90:93]
	v_mfma_f32_16x16x32_bf16 v[86:89], v[234:237], v[210:213], v[86:89]
	v_mfma_f32_16x16x32_bf16 v[82:85], v[242:245], v[210:213], v[82:85]
	v_mfma_f32_16x16x32_bf16 v[78:81], v[234:237], v[218:221], v[78:81]
	v_mfma_f32_16x16x32_bf16 v[74:77], v[242:245], v[218:221], v[74:77]
	v_mfma_f32_16x16x32_bf16 v[70:73], v[234:237], v[226:229], v[70:73]
	v_mfma_f32_16x16x32_bf16 v[66:69], v[242:245], v[226:229], v[66:69]
	v_readfirstlane_b32 s61, v144
	v_lshl_add_u64 v[180:181], v[180:181], 0, s[30:31]
	s_mov_b32 m0, s61
	v_readfirstlane_b32 s61, v145
	s_barrier
	ds_read_b128 v[176:179], v193 offset:49152
	ds_read_b128 v[202:205], v193 offset:50176
	ds_read_b128 v[206:209], v194 offset:49152
	ds_read_b128 v[210:213], v194 offset:50176
	ds_read_b128 v[214:217], v195 offset:49152
	ds_read_b128 v[218:221], v195 offset:50176
	ds_read_b128 v[222:225], v196 offset:49152
	ds_read_b128 v[226:229], v196 offset:50176
	global_load_lds_dwordx4 v[180:181], off
	v_lshl_add_u64 v[180:181], v[246:247], 0, s[30:31]
	s_mov_b32 m0, s61
	s_nop 0
	global_load_lds_dwordx4 v[180:181], off
	s_barrier
	s_waitcnt lgkmcnt(0)
	s_waitcnt lgkmcnt(0)
	v_mfma_f32_16x16x32_bf16 v[62:65], v[150:153], v[176:179], v[62:65]
	v_mfma_f32_16x16x32_bf16 v[58:61], v[158:161], v[176:179], v[58:61]
	v_mfma_f32_16x16x32_bf16 v[54:57], v[150:153], v[206:209], v[54:57]
	v_mfma_f32_16x16x32_bf16 v[50:53], v[158:161], v[206:209], v[50:53]
	v_mfma_f32_16x16x32_bf16 v[46:49], v[150:153], v[214:217], v[46:49]
	v_mfma_f32_16x16x32_bf16 v[42:45], v[158:161], v[214:217], v[42:45]
	v_mfma_f32_16x16x32_bf16 v[38:41], v[150:153], v[222:225], v[38:41]
	v_mfma_f32_16x16x32_bf16 v[34:37], v[158:161], v[222:225], v[34:37]
	v_mfma_f32_16x16x32_bf16 v[62:65], v[154:157], v[202:205], v[62:65]
	v_mfma_f32_16x16x32_bf16 v[58:61], v[172:175], v[202:205], v[58:61]
	v_mfma_f32_16x16x32_bf16 v[54:57], v[154:157], v[210:213], v[54:57]
	v_mfma_f32_16x16x32_bf16 v[50:53], v[172:175], v[210:213], v[50:53]
	v_mfma_f32_16x16x32_bf16 v[46:49], v[154:157], v[218:221], v[46:49]
	v_mfma_f32_16x16x32_bf16 v[42:45], v[172:175], v[218:221], v[42:45]
	v_mfma_f32_16x16x32_bf16 v[38:41], v[154:157], v[226:229], v[38:41]
	v_mfma_f32_16x16x32_bf16 v[34:37], v[172:175], v[226:229], v[34:37]
	s_barrier
	v_readfirstlane_b32 s61, v146
	v_lshl_add_u64 v[150:151], v[248:249], 0, s[34:35]
	s_mov_b32 m0, s61
	v_readfirstlane_b32 s61, v147
	global_load_lds_dwordx4 v[150:151], off
	v_lshl_add_u64 v[150:151], v[250:251], 0, s[34:35]
	s_mov_b32 m0, s61
	s_nop 0
	global_load_lds_dwordx4 v[150:151], off
	s_waitcnt vmcnt(6)
	s_barrier
	v_mfma_f32_16x16x32_bf16 v[30:33], v[230:233], v[176:179], v[30:33]
	v_mfma_f32_16x16x32_bf16 v[26:29], v[238:241], v[176:179], v[26:29]
	v_mfma_f32_16x16x32_bf16 v[22:25], v[230:233], v[206:209], v[22:25]
	v_mfma_f32_16x16x32_bf16 v[18:21], v[238:241], v[206:209], v[18:21]
	v_mfma_f32_16x16x32_bf16 v[14:17], v[230:233], v[214:217], v[14:17]
	v_mfma_f32_16x16x32_bf16 v[10:13], v[238:241], v[214:217], v[10:13]
	v_mfma_f32_16x16x32_bf16 v[6:9], v[230:233], v[222:225], v[6:9]
	v_mfma_f32_16x16x32_bf16 v[2:5], v[238:241], v[222:225], v[2:5]
	v_mfma_f32_16x16x32_bf16 v[30:33], v[234:237], v[202:205], v[30:33]
	v_mfma_f32_16x16x32_bf16 v[26:29], v[242:245], v[202:205], v[26:29]
	v_mfma_f32_16x16x32_bf16 v[22:25], v[234:237], v[210:213], v[22:25]
	v_mfma_f32_16x16x32_bf16 v[18:21], v[242:245], v[210:213], v[18:21]
	v_mfma_f32_16x16x32_bf16 v[14:17], v[234:237], v[218:221], v[14:17]
	v_mfma_f32_16x16x32_bf16 v[10:13], v[242:245], v[218:221], v[10:13]
	v_mfma_f32_16x16x32_bf16 v[6:9], v[234:237], v[226:229], v[6:9]
	v_mfma_f32_16x16x32_bf16 v[2:5], v[242:245], v[226:229], v[2:5]
	s_add_i32 s39, s39, 2
	s_add_u32 s62, s62, 0x100
	s_addc_u32 s63, s63, 0
	s_cmp_lt_u32 s39, 12
	s_barrier
	s_cbranch_scc1 .LBB0_2359
	v_readfirstlane_b32 s39, v148
	v_lshl_add_u64 v[130:131], v[130:131], 0, s[36:37]
	s_mov_b32 m0, s39
	v_readfirstlane_b32 s39, v149
	ds_read_b128 v[134:137], v192
	ds_read_b128 v[138:141], v192 offset:1024
	ds_read_b128 v[142:145], v192 offset:2048
	ds_read_b128 v[150:153], v192 offset:3072
	ds_read_b128 v[154:157], v193
	ds_read_b128 v[158:161], v193 offset:1024
	ds_read_b128 v[172:175], v194
	ds_read_b128 v[176:179], v194 offset:1024
	ds_read_b128 v[202:205], v195
	ds_read_b128 v[206:209], v195 offset:1024
	ds_read_b128 v[210:213], v196
	ds_read_b128 v[214:217], v196 offset:1024
	global_load_lds_dwordx4 v[130:131], off
	v_lshl_add_u64 v[130:131], v[132:133], 0, s[36:37]
	s_mov_b32 m0, s39
	s_nop 0
	global_load_lds_dwordx4 v[130:131], off
	s_barrier
	s_waitcnt lgkmcnt(0)
	s_setprio 1
	s_waitcnt lgkmcnt(0)
	v_mfma_f32_16x16x32_bf16 v[126:129], v[134:137], v[154:157], v[126:129]
	v_mfma_f32_16x16x32_bf16 v[122:125], v[142:145], v[154:157], v[122:125]
	v_mfma_f32_16x16x32_bf16 v[118:121], v[134:137], v[172:175], v[118:121]
	v_mfma_f32_16x16x32_bf16 v[114:117], v[142:145], v[172:175], v[114:117]
	v_mfma_f32_16x16x32_bf16 v[110:113], v[134:137], v[202:205], v[110:113]
	v_mfma_f32_16x16x32_bf16 v[106:109], v[142:145], v[202:205], v[106:109]
	v_mfma_f32_16x16x32_bf16 v[102:105], v[134:137], v[210:213], v[102:105]
	v_mfma_f32_16x16x32_bf16 v[98:101], v[142:145], v[210:213], v[98:101]
	v_mfma_f32_16x16x32_bf16 v[126:129], v[138:141], v[158:161], v[126:129]
	v_mfma_f32_16x16x32_bf16 v[122:125], v[150:153], v[158:161], v[122:125]
	v_mfma_f32_16x16x32_bf16 v[118:121], v[138:141], v[176:179], v[118:121]
	v_mfma_f32_16x16x32_bf16 v[114:117], v[150:153], v[176:179], v[114:117]
	v_mfma_f32_16x16x32_bf16 v[110:113], v[138:141], v[206:209], v[110:113]
	v_mfma_f32_16x16x32_bf16 v[106:109], v[150:153], v[206:209], v[106:109]
	v_mfma_f32_16x16x32_bf16 v[102:105], v[138:141], v[214:217], v[102:105]
	v_mfma_f32_16x16x32_bf16 v[98:101], v[150:153], v[214:217], v[98:101]
	s_setprio 0
	s_barrier
	ds_read_b128 v[130:133], v197
	ds_read_b128 v[146:149], v197 offset:1024
	ds_read_b128 v[218:221], v197 offset:2048
	ds_read_b128 v[222:225], v197 offset:3072
	s_barrier
	s_waitcnt lgkmcnt(0)
	s_setprio 1
	s_waitcnt lgkmcnt(0)
	v_mfma_f32_16x16x32_bf16 v[94:97], v[130:133], v[154:157], v[94:97]
	v_mfma_f32_16x16x32_bf16 v[90:93], v[218:221], v[154:157], v[90:93]
	v_mfma_f32_16x16x32_bf16 v[86:89], v[130:133], v[172:175], v[86:89]
	v_mfma_f32_16x16x32_bf16 v[82:85], v[218:221], v[172:175], v[82:85]
	v_mfma_f32_16x16x32_bf16 v[78:81], v[130:133], v[202:205], v[78:81]
	v_mfma_f32_16x16x32_bf16 v[74:77], v[218:221], v[202:205], v[74:77]
	v_mfma_f32_16x16x32_bf16 v[70:73], v[130:133], v[210:213], v[70:73]
	v_mfma_f32_16x16x32_bf16 v[66:69], v[218:221], v[210:213], v[66:69]
	v_mfma_f32_16x16x32_bf16 v[94:97], v[146:149], v[158:161], v[94:97]
	v_mfma_f32_16x16x32_bf16 v[90:93], v[222:225], v[158:161], v[90:93]
	v_mfma_f32_16x16x32_bf16 v[86:89], v[146:149], v[176:179], v[86:89]
	v_mfma_f32_16x16x32_bf16 v[82:85], v[222:225], v[176:179], v[82:85]
	v_mfma_f32_16x16x32_bf16 v[78:81], v[146:149], v[206:209], v[78:81]
	v_mfma_f32_16x16x32_bf16 v[74:77], v[222:225], v[206:209], v[74:77]
	v_mfma_f32_16x16x32_bf16 v[70:73], v[146:149], v[214:217], v[70:73]
	v_mfma_f32_16x16x32_bf16 v[66:69], v[222:225], v[214:217], v[66:69]
	s_setprio 0
	s_barrier
	ds_read_b128 v[154:157], v193 offset:16384
	ds_read_b128 v[158:161], v193 offset:17408
	ds_read_b128 v[172:175], v194 offset:16384
	ds_read_b128 v[176:179], v194 offset:17408
	ds_read_b128 v[202:205], v195 offset:16384
	ds_read_b128 v[206:209], v195 offset:17408
	ds_read_b128 v[210:213], v196 offset:16384
	ds_read_b128 v[214:217], v196 offset:17408
	s_waitcnt vmcnt(4)
	s_barrier
	s_waitcnt lgkmcnt(0)
	s_setprio 1
	s_waitcnt lgkmcnt(0)
	v_mfma_f32_16x16x32_bf16 v[62:65], v[134:137], v[154:157], v[62:65]
	v_mfma_f32_16x16x32_bf16 v[58:61], v[142:145], v[154:157], v[58:61]
	v_mfma_f32_16x16x32_bf16 v[54:57], v[134:137], v[172:175], v[54:57]
	v_mfma_f32_16x16x32_bf16 v[50:53], v[142:145], v[172:175], v[50:53]
	v_mfma_f32_16x16x32_bf16 v[46:49], v[134:137], v[202:205], v[46:49]
	v_mfma_f32_16x16x32_bf16 v[42:45], v[142:145], v[202:205], v[42:45]
	v_mfma_f32_16x16x32_bf16 v[38:41], v[134:137], v[210:213], v[38:41]
	v_mfma_f32_16x16x32_bf16 v[34:37], v[142:145], v[210:213], v[34:37]
	v_mfma_f32_16x16x32_bf16 v[62:65], v[138:141], v[158:161], v[62:65]
	v_mfma_f32_16x16x32_bf16 v[58:61], v[150:153], v[158:161], v[58:61]
	v_mfma_f32_16x16x32_bf16 v[54:57], v[138:141], v[176:179], v[54:57]
	v_mfma_f32_16x16x32_bf16 v[50:53], v[150:153], v[176:179], v[50:53]
	v_mfma_f32_16x16x32_bf16 v[46:49], v[138:141], v[206:209], v[46:49]
	v_mfma_f32_16x16x32_bf16 v[42:45], v[150:153], v[206:209], v[42:45]
	v_mfma_f32_16x16x32_bf16 v[38:41], v[138:141], v[214:217], v[38:41]
	v_mfma_f32_16x16x32_bf16 v[34:37], v[150:153], v[214:217], v[34:37]
	s_setprio 0
	s_setprio 1
	v_mfma_f32_16x16x32_bf16 v[30:33], v[130:133], v[154:157], v[30:33]
	v_mfma_f32_16x16x32_bf16 v[26:29], v[218:221], v[154:157], v[26:29]
	v_mfma_f32_16x16x32_bf16 v[22:25], v[130:133], v[172:175], v[22:25]
	v_mfma_f32_16x16x32_bf16 v[18:21], v[218:221], v[172:175], v[18:21]
	v_mfma_f32_16x16x32_bf16 v[14:17], v[130:133], v[202:205], v[14:17]
	v_mfma_f32_16x16x32_bf16 v[10:13], v[218:221], v[202:205], v[10:13]
	v_mfma_f32_16x16x32_bf16 v[6:9], v[130:133], v[210:213], v[6:9]
	v_mfma_f32_16x16x32_bf16 v[2:5], v[218:221], v[210:213], v[2:5]
	v_mfma_f32_16x16x32_bf16 v[30:33], v[146:149], v[158:161], v[30:33]
	v_mfma_f32_16x16x32_bf16 v[26:29], v[222:225], v[158:161], v[26:29]
	v_mfma_f32_16x16x32_bf16 v[22:25], v[146:149], v[176:179], v[22:25]
	v_mfma_f32_16x16x32_bf16 v[18:21], v[222:225], v[176:179], v[18:21]
	v_mfma_f32_16x16x32_bf16 v[14:17], v[146:149], v[206:209], v[14:17]
	v_mfma_f32_16x16x32_bf16 v[10:13], v[222:225], v[206:209], v[10:13]
	v_mfma_f32_16x16x32_bf16 v[6:9], v[146:149], v[214:217], v[6:9]
	v_mfma_f32_16x16x32_bf16 v[2:5], v[222:225], v[214:217], v[2:5]
	s_setprio 0
	s_barrier
	ds_read_b128 v[172:175], v199
	ds_read_b128 v[176:179], v199 offset:1024
	ds_read_b128 v[202:205], v199 offset:2048
	ds_read_b128 v[206:209], v199 offset:3072
	ds_read_b128 v[130:133], v193 offset:32768
	ds_read_b128 v[134:137], v193 offset:33792
	ds_read_b128 v[210:213], v194 offset:32768
	ds_read_b128 v[214:217], v194 offset:33792
	ds_read_b128 v[218:221], v195 offset:32768
	ds_read_b128 v[222:225], v195 offset:33792
	ds_read_b128 v[226:229], v196 offset:32768
	ds_read_b128 v[230:233], v196 offset:33792
	s_waitcnt vmcnt(2)
	s_barrier
	s_waitcnt lgkmcnt(0)
	s_setprio 1
	s_waitcnt lgkmcnt(0)
	v_mfma_f32_16x16x32_bf16 v[126:129], v[172:175], v[130:133], v[126:129]
	v_mfma_f32_16x16x32_bf16 v[122:125], v[202:205], v[130:133], v[122:125]
	v_mfma_f32_16x16x32_bf16 v[118:121], v[172:175], v[210:213], v[118:121]
	v_mfma_f32_16x16x32_bf16 v[114:117], v[202:205], v[210:213], v[114:117]
	v_mfma_f32_16x16x32_bf16 v[110:113], v[172:175], v[218:221], v[110:113]
	v_mfma_f32_16x16x32_bf16 v[106:109], v[202:205], v[218:221], v[106:109]
	v_mfma_f32_16x16x32_bf16 v[102:105], v[172:175], v[226:229], v[102:105]
	v_mfma_f32_16x16x32_bf16 v[98:101], v[202:205], v[226:229], v[98:101]
	v_mfma_f32_16x16x32_bf16 v[158:161], v[176:179], v[134:137], v[126:129]
	v_mfma_f32_16x16x32_bf16 v[154:157], v[206:209], v[134:137], v[122:125]
	v_mfma_f32_16x16x32_bf16 v[142:145], v[176:179], v[214:217], v[118:121]
	v_mfma_f32_16x16x32_bf16 v[138:141], v[206:209], v[214:217], v[114:117]
	v_mfma_f32_16x16x32_bf16 v[126:129], v[176:179], v[222:225], v[110:113]
	v_mfma_f32_16x16x32_bf16 v[122:125], v[206:209], v[222:225], v[106:109]
	v_mfma_f32_16x16x32_bf16 v[110:113], v[176:179], v[230:233], v[102:105]
	v_mfma_f32_16x16x32_bf16 v[106:109], v[206:209], v[230:233], v[98:101]
	s_setprio 0
	s_barrier
	ds_read_b128 v[234:237], v200
	ds_read_b128 v[238:241], v200 offset:1024
	ds_read_b128 v[242:245], v200 offset:2048
	ds_read_b128 v[246:249], v200 offset:3072
	s_waitcnt vmcnt(0)
	s_barrier
	s_waitcnt lgkmcnt(0)
	s_setprio 1
	s_waitcnt lgkmcnt(0)
	v_mfma_f32_16x16x32_bf16 v[94:97], v[234:237], v[130:133], v[94:97]
	v_mfma_f32_16x16x32_bf16 v[90:93], v[242:245], v[130:133], v[90:93]
	v_mfma_f32_16x16x32_bf16 v[86:89], v[234:237], v[210:213], v[86:89]
	v_mfma_f32_16x16x32_bf16 v[82:85], v[242:245], v[210:213], v[82:85]
	v_mfma_f32_16x16x32_bf16 v[78:81], v[234:237], v[218:221], v[78:81]
	v_mfma_f32_16x16x32_bf16 v[74:77], v[242:245], v[218:221], v[74:77]
	v_mfma_f32_16x16x32_bf16 v[70:73], v[234:237], v[226:229], v[70:73]
	v_mfma_f32_16x16x32_bf16 v[66:69], v[242:245], v[226:229], v[66:69]
	v_mfma_f32_16x16x32_bf16 v[150:153], v[238:241], v[134:137], v[94:97]
	v_mfma_f32_16x16x32_bf16 v[146:149], v[246:249], v[134:137], v[90:93]
	v_mfma_f32_16x16x32_bf16 v[134:137], v[238:241], v[214:217], v[86:89]
	v_mfma_f32_16x16x32_bf16 v[130:133], v[246:249], v[214:217], v[82:85]
	v_mfma_f32_16x16x32_bf16 v[118:121], v[238:241], v[222:225], v[78:81]
	v_mfma_f32_16x16x32_bf16 v[114:117], v[246:249], v[222:225], v[74:77]
	v_mfma_f32_16x16x32_bf16 v[102:105], v[238:241], v[230:233], v[70:73]
	v_mfma_f32_16x16x32_bf16 v[98:101], v[246:249], v[230:233], v[66:69]
	s_setprio 0
	s_barrier
	s_nop 0
	ds_read_b128 v[66:69], v193 offset:49152
	ds_read_b128 v[70:73], v193 offset:50176
	ds_read_b128 v[210:213], v194 offset:49152
	ds_read_b128 v[214:217], v194 offset:50176
	ds_read_b128 v[218:221], v195 offset:49152
	ds_read_b128 v[222:225], v195 offset:50176
	ds_read_b128 v[226:229], v196 offset:49152
	ds_read_b128 v[230:233], v196 offset:50176
	s_barrier
	s_waitcnt lgkmcnt(0)
	s_setprio 1
	s_waitcnt lgkmcnt(0)
	v_mfma_f32_16x16x32_bf16 v[62:65], v[172:175], v[66:69], v[62:65]
	v_mfma_f32_16x16x32_bf16 v[58:61], v[202:205], v[66:69], v[58:61]
	v_mfma_f32_16x16x32_bf16 v[54:57], v[172:175], v[210:213], v[54:57]
	v_mfma_f32_16x16x32_bf16 v[50:53], v[202:205], v[210:213], v[50:53]
	v_mfma_f32_16x16x32_bf16 v[46:49], v[172:175], v[218:221], v[46:49]
	v_mfma_f32_16x16x32_bf16 v[42:45], v[202:205], v[218:221], v[42:45]
	v_mfma_f32_16x16x32_bf16 v[38:41], v[172:175], v[226:229], v[38:41]
	v_mfma_f32_16x16x32_bf16 v[34:37], v[202:205], v[226:229], v[34:37]
	v_mfma_f32_16x16x32_bf16 v[94:97], v[176:179], v[70:73], v[62:65]
	v_mfma_f32_16x16x32_bf16 v[90:93], v[206:209], v[70:73], v[58:61]
	v_mfma_f32_16x16x32_bf16 v[78:81], v[176:179], v[214:217], v[54:57]
	v_mfma_f32_16x16x32_bf16 v[74:77], v[206:209], v[214:217], v[50:53]
	v_mfma_f32_16x16x32_bf16 v[62:65], v[176:179], v[222:225], v[46:49]
	v_mfma_f32_16x16x32_bf16 v[58:61], v[206:209], v[222:225], v[42:45]
	v_mfma_f32_16x16x32_bf16 v[46:49], v[176:179], v[230:233], v[38:41]
	v_mfma_f32_16x16x32_bf16 v[42:45], v[206:209], v[230:233], v[34:37]
	s_setprio 0
	s_setprio 1
	v_mfma_f32_16x16x32_bf16 v[30:33], v[234:237], v[66:69], v[30:33]
	v_mfma_f32_16x16x32_bf16 v[26:29], v[242:245], v[66:69], v[26:29]
	v_mfma_f32_16x16x32_bf16 v[22:25], v[234:237], v[210:213], v[22:25]
	v_mfma_f32_16x16x32_bf16 v[18:21], v[242:245], v[210:213], v[18:21]
	v_mfma_f32_16x16x32_bf16 v[14:17], v[234:237], v[218:221], v[14:17]
	v_mfma_f32_16x16x32_bf16 v[10:13], v[242:245], v[218:221], v[10:13]
	v_mfma_f32_16x16x32_bf16 v[6:9], v[234:237], v[226:229], v[6:9]
	v_mfma_f32_16x16x32_bf16 v[2:5], v[242:245], v[226:229], v[2:5]
	v_mfma_f32_16x16x32_bf16 v[86:89], v[238:241], v[70:73], v[30:33]
	v_mfma_f32_16x16x32_bf16 v[82:85], v[246:249], v[70:73], v[26:29]
	v_mfma_f32_16x16x32_bf16 v[70:73], v[238:241], v[214:217], v[22:25]
	v_mfma_f32_16x16x32_bf16 v[66:69], v[246:249], v[214:217], v[18:21]
	v_mfma_f32_16x16x32_bf16 v[54:57], v[238:241], v[222:225], v[14:17]
	v_mfma_f32_16x16x32_bf16 v[50:53], v[246:249], v[222:225], v[10:13]
	v_mfma_f32_16x16x32_bf16 v[38:41], v[238:241], v[230:233], v[6:9]
	v_mfma_f32_16x16x32_bf16 v[34:37], v[246:249], v[230:233], v[2:5]
	s_setprio 0
	s_barrier
	s_and_saveexec_b64 s[62:63], s[6:7]
	s_cbranch_execz .LBB0_2362
	s_barrier
